# P1 K-loop: DMA staging in saddr+voffset form (16 VALU address adds per 2 K-tiles removed), ds_reads as M0 fillers
# baseline (speedup 1.0000x reference)
.LBB0_134:
	s_add_u32 s0, s34, 0xfff00080
	s_addc_u32 s1, s35, -1
	s_cmp_eq_u32 s60, 60
	s_cselect_b32 s39, s12, s1
	s_cselect_b32 s38, s13, s0
	s_cselect_b32 s37, s15, s59
	s_cselect_b32 s36, s57, s58
	s_add_i32 m0, s29, 0xc000
	ds_read_b128 v[148:151], v156
	global_load_lds_dwordx4 v140, s[34:35]
	s_add_i32 m0, s29, 0xe000
	ds_read_b128 v[160:163], v156 offset:1024
	global_load_lds_dwordx4 v142, s[34:35]
	ds_read_b128 v[164:167], v156 offset:2048
	ds_read_b128 v[168:171], v156 offset:3072
	ds_read_b128 v[172:175], v157
	ds_read_b128 v[176:179], v157 offset:1024
	ds_read_b128 v[180:183], v157 offset:2048
	ds_read_b128 v[184:187], v157 offset:3072
	ds_read_b128 v[188:191], v158
	ds_read_b128 v[192:195], v158 offset:1024
	ds_read_b128 v[196:199], v158 offset:2048
	ds_read_b128 v[200:203], v158 offset:3072
	ds_read_b128 v[208:211], v158 offset:4096
	ds_read_b128 v[212:215], v158 offset:5120
	ds_read_b128 v[216:219], v158 offset:6144
	ds_read_b128 v[220:223], v158 offset:7168
	s_waitcnt vmcnt(8)
	s_waitcnt lgkmcnt(0)
	s_setprio 3
	s_barrier
	v_mfma_f32_16x16x32_bf16 v[124:127], v[148:151], v[188:191], v[124:127]
	v_mfma_f32_16x16x32_bf16 v[120:123], v[164:167], v[188:191], v[120:123]
	v_mfma_f32_16x16x32_bf16 v[108:111], v[148:151], v[196:199], v[108:111]
	v_mfma_f32_16x16x32_bf16 v[104:107], v[164:167], v[196:199], v[104:107]
	v_mfma_f32_16x16x32_bf16 v[92:95], v[148:151], v[208:211], v[92:95]
	v_mfma_f32_16x16x32_bf16 v[88:91], v[164:167], v[208:211], v[88:91]
	v_mfma_f32_16x16x32_bf16 v[76:79], v[148:151], v[216:219], v[76:79]
	v_mfma_f32_16x16x32_bf16 v[72:75], v[164:167], v[216:219], v[72:75]
	v_mfma_f32_16x16x32_bf16 v[124:127], v[160:163], v[192:195], v[124:127]
	v_mfma_f32_16x16x32_bf16 v[120:123], v[168:171], v[192:195], v[120:123]
	v_mfma_f32_16x16x32_bf16 v[108:111], v[160:163], v[200:203], v[108:111]
	v_mfma_f32_16x16x32_bf16 v[104:107], v[168:171], v[200:203], v[104:107]
	v_mfma_f32_16x16x32_bf16 v[92:95], v[160:163], v[212:215], v[92:95]
	v_mfma_f32_16x16x32_bf16 v[88:91], v[168:171], v[212:215], v[88:91]
	v_mfma_f32_16x16x32_bf16 v[76:79], v[160:163], v[220:223], v[76:79]
	v_mfma_f32_16x16x32_bf16 v[72:75], v[168:171], v[220:223], v[72:75]
	s_setprio 0
	s_setprio 3
	v_mfma_f32_16x16x32_bf16 v[116:119], v[172:175], v[188:191], v[116:119]
	v_mfma_f32_16x16x32_bf16 v[112:115], v[180:183], v[188:191], v[112:115]
	v_mfma_f32_16x16x32_bf16 v[100:103], v[172:175], v[196:199], v[100:103]
	v_mfma_f32_16x16x32_bf16 v[96:99], v[180:183], v[196:199], v[96:99]
	v_mfma_f32_16x16x32_bf16 v[84:87], v[172:175], v[208:211], v[84:87]
	v_mfma_f32_16x16x32_bf16 v[80:83], v[180:183], v[208:211], v[80:83]
	v_mfma_f32_16x16x32_bf16 v[68:71], v[172:175], v[216:219], v[68:71]
	v_mfma_f32_16x16x32_bf16 v[64:67], v[180:183], v[216:219], v[64:67]
	v_mfma_f32_16x16x32_bf16 v[116:119], v[176:179], v[192:195], v[116:119]
	v_mfma_f32_16x16x32_bf16 v[112:115], v[184:187], v[192:195], v[112:115]
	v_mfma_f32_16x16x32_bf16 v[100:103], v[176:179], v[200:203], v[100:103]
	v_mfma_f32_16x16x32_bf16 v[96:99], v[184:187], v[200:203], v[96:99]
	v_mfma_f32_16x16x32_bf16 v[84:87], v[176:179], v[212:215], v[84:87]
	v_mfma_f32_16x16x32_bf16 v[80:83], v[184:187], v[212:215], v[80:83]
	v_mfma_f32_16x16x32_bf16 v[68:71], v[176:179], v[220:223], v[68:71]
	v_mfma_f32_16x16x32_bf16 v[64:67], v[184:187], v[220:223], v[64:67]
	s_barrier
	s_setprio 0
	s_add_i32 s0, s51, s41
	s_mov_b32 m0, s0
	ds_read_b128 v[188:191], v158 offset:16384
	global_load_lds_dwordx4 v132, s[36:37]
	s_add_i32 m0, s0, 0x2000
	ds_read_b128 v[192:195], v158 offset:17408
	global_load_lds_dwordx4 v136, s[36:37]
	s_add_u32 s62, s36, 0x100000
	s_addc_u32 s63, s37, 0
	s_add_i32 s0, s52, s41
	s_mov_b32 m0, s0
	ds_read_b128 v[196:199], v158 offset:18432
	global_load_lds_dwordx4 v132, s[62:63]
	s_add_i32 m0, s0, 0x2000
	ds_read_b128 v[200:203], v158 offset:19456
	global_load_lds_dwordx4 v136, s[62:63]
	s_mov_b32 m0, s29
	ds_read_b128 v[208:211], v158 offset:20480
	global_load_lds_dwordx4 v130, s[38:39]
	s_mov_b32 m0, s31
	ds_read_b128 v[212:215], v158 offset:21504
	global_load_lds_dwordx4 v134, s[38:39]
	ds_read_b128 v[216:219], v158 offset:22528
	ds_read_b128 v[220:223], v158 offset:23552
	s_waitcnt vmcnt(8)
	s_waitcnt lgkmcnt(0)
	s_setprio 3
	s_barrier
	v_mfma_f32_16x16x32_bf16 v[60:63], v[148:151], v[188:191], v[60:63]
	v_mfma_f32_16x16x32_bf16 v[56:59], v[164:167], v[188:191], v[56:59]
	v_mfma_f32_16x16x32_bf16 v[44:47], v[148:151], v[196:199], v[44:47]
	v_mfma_f32_16x16x32_bf16 v[40:43], v[164:167], v[196:199], v[40:43]
	v_mfma_f32_16x16x32_bf16 v[28:31], v[148:151], v[208:211], v[28:31]
	v_mfma_f32_16x16x32_bf16 v[24:27], v[164:167], v[208:211], v[24:27]
	v_mfma_f32_16x16x32_bf16 v[12:15], v[148:151], v[216:219], v[12:15]
	v_mfma_f32_16x16x32_bf16 v[8:11], v[164:167], v[216:219], v[8:11]
	v_mfma_f32_16x16x32_bf16 v[60:63], v[160:163], v[192:195], v[60:63]
	v_mfma_f32_16x16x32_bf16 v[56:59], v[168:171], v[192:195], v[56:59]
	v_mfma_f32_16x16x32_bf16 v[44:47], v[160:163], v[200:203], v[44:47]
	v_mfma_f32_16x16x32_bf16 v[40:43], v[168:171], v[200:203], v[40:43]
	v_mfma_f32_16x16x32_bf16 v[28:31], v[160:163], v[212:215], v[28:31]
	v_mfma_f32_16x16x32_bf16 v[24:27], v[168:171], v[212:215], v[24:27]
	v_mfma_f32_16x16x32_bf16 v[12:15], v[160:163], v[220:223], v[12:15]
	v_mfma_f32_16x16x32_bf16 v[8:11], v[168:171], v[220:223], v[8:11]
	s_setprio 0
	s_setprio 3
	v_mfma_f32_16x16x32_bf16 v[52:55], v[172:175], v[188:191], v[52:55]
	v_mfma_f32_16x16x32_bf16 v[48:51], v[180:183], v[188:191], v[48:51]
	v_mfma_f32_16x16x32_bf16 v[36:39], v[172:175], v[196:199], v[36:39]
	v_mfma_f32_16x16x32_bf16 v[32:35], v[180:183], v[196:199], v[32:35]
	v_mfma_f32_16x16x32_bf16 v[20:23], v[172:175], v[208:211], v[20:23]
	v_mfma_f32_16x16x32_bf16 v[16:19], v[180:183], v[208:211], v[16:19]
	v_mfma_f32_16x16x32_bf16 v[4:7], v[172:175], v[216:219], v[4:7]
	v_mfma_f32_16x16x32_bf16 v[0:3], v[180:183], v[216:219], v[0:3]
	v_mfma_f32_16x16x32_bf16 v[52:55], v[176:179], v[192:195], v[52:55]
	v_mfma_f32_16x16x32_bf16 v[48:51], v[184:187], v[192:195], v[48:51]
	v_mfma_f32_16x16x32_bf16 v[36:39], v[176:179], v[200:203], v[36:39]
	v_mfma_f32_16x16x32_bf16 v[32:35], v[184:187], v[200:203], v[32:35]
	v_mfma_f32_16x16x32_bf16 v[20:23], v[176:179], v[212:215], v[20:23]
	v_mfma_f32_16x16x32_bf16 v[16:19], v[184:187], v[212:215], v[16:19]
	v_mfma_f32_16x16x32_bf16 v[4:7], v[176:179], v[220:223], v[4:7]
	v_mfma_f32_16x16x32_bf16 v[0:3], v[184:187], v[220:223], v[0:3]
	s_barrier
	s_setprio 0
	s_add_i32 s0, 0, 0x18000
	v_add_u32_e32 v128, s0, v153
	s_add_i32 s1, 0, 0x1c000
	ds_read_b128 v[148:151], v128
	ds_read_b128 v[160:163], v128 offset:1024
	ds_read_b128 v[164:167], v128 offset:2048
	ds_read_b128 v[168:171], v128 offset:3072
	v_add_u32_e32 v128, s1, v153
	ds_read_b128 v[172:175], v128
	ds_read_b128 v[176:179], v128 offset:1024
	ds_read_b128 v[180:183], v128 offset:2048
	ds_read_b128 v[184:187], v128 offset:3072
	s_add_u32 s38, s38, 0x100000
	s_addc_u32 s39, s39, 0
	s_mov_b32 m0, s42
	ds_read_b128 v[188:191], v158 offset:32768
	global_load_lds_dwordx4 v130, s[38:39]
	s_mov_b32 m0, s43
	ds_read_b128 v[192:195], v158 offset:33792
	global_load_lds_dwordx4 v134, s[38:39]
	ds_read_b128 v[196:199], v158 offset:34816
	ds_read_b128 v[200:203], v158 offset:35840
	ds_read_b128 v[208:211], v158 offset:36864
	ds_read_b128 v[212:215], v158 offset:37888
	ds_read_b128 v[216:219], v158 offset:38912
	ds_read_b128 v[220:223], v158 offset:39936
	s_waitcnt vmcnt(8)
	s_waitcnt lgkmcnt(0)
	s_setprio 3
	s_barrier
	v_mfma_f32_16x16x32_bf16 v[124:127], v[148:151], v[188:191], v[124:127]
	v_mfma_f32_16x16x32_bf16 v[120:123], v[164:167], v[188:191], v[120:123]
	v_mfma_f32_16x16x32_bf16 v[108:111], v[148:151], v[196:199], v[108:111]
	v_mfma_f32_16x16x32_bf16 v[104:107], v[164:167], v[196:199], v[104:107]
	v_mfma_f32_16x16x32_bf16 v[92:95], v[148:151], v[208:211], v[92:95]
	v_mfma_f32_16x16x32_bf16 v[88:91], v[164:167], v[208:211], v[88:91]
	v_mfma_f32_16x16x32_bf16 v[76:79], v[148:151], v[216:219], v[76:79]
	v_mfma_f32_16x16x32_bf16 v[72:75], v[164:167], v[216:219], v[72:75]
	v_mfma_f32_16x16x32_bf16 v[124:127], v[160:163], v[192:195], v[124:127]
	v_mfma_f32_16x16x32_bf16 v[120:123], v[168:171], v[192:195], v[120:123]
	v_mfma_f32_16x16x32_bf16 v[108:111], v[160:163], v[200:203], v[108:111]
	v_mfma_f32_16x16x32_bf16 v[104:107], v[168:171], v[200:203], v[104:107]
	v_mfma_f32_16x16x32_bf16 v[92:95], v[160:163], v[212:215], v[92:95]
	v_mfma_f32_16x16x32_bf16 v[88:91], v[168:171], v[212:215], v[88:91]
	v_mfma_f32_16x16x32_bf16 v[76:79], v[160:163], v[220:223], v[76:79]
	v_mfma_f32_16x16x32_bf16 v[72:75], v[168:171], v[220:223], v[72:75]
	s_setprio 0
	s_setprio 3
	v_mfma_f32_16x16x32_bf16 v[116:119], v[172:175], v[188:191], v[116:119]
	v_mfma_f32_16x16x32_bf16 v[112:115], v[180:183], v[188:191], v[112:115]
	v_mfma_f32_16x16x32_bf16 v[100:103], v[172:175], v[196:199], v[100:103]
	v_mfma_f32_16x16x32_bf16 v[96:99], v[180:183], v[196:199], v[96:99]
	v_mfma_f32_16x16x32_bf16 v[84:87], v[172:175], v[208:211], v[84:87]
	v_mfma_f32_16x16x32_bf16 v[80:83], v[180:183], v[208:211], v[80:83]
	v_mfma_f32_16x16x32_bf16 v[68:71], v[172:175], v[216:219], v[68:71]
	v_mfma_f32_16x16x32_bf16 v[64:67], v[180:183], v[216:219], v[64:67]
	v_mfma_f32_16x16x32_bf16 v[116:119], v[176:179], v[192:195], v[116:119]
	v_mfma_f32_16x16x32_bf16 v[112:115], v[184:187], v[192:195], v[112:115]
	v_mfma_f32_16x16x32_bf16 v[100:103], v[176:179], v[200:203], v[100:103]
	v_mfma_f32_16x16x32_bf16 v[96:99], v[184:187], v[200:203], v[96:99]
	v_mfma_f32_16x16x32_bf16 v[84:87], v[176:179], v[212:215], v[84:87]
	v_mfma_f32_16x16x32_bf16 v[80:83], v[184:187], v[212:215], v[80:83]
	v_mfma_f32_16x16x32_bf16 v[68:71], v[176:179], v[220:223], v[68:71]
	v_mfma_f32_16x16x32_bf16 v[64:67], v[184:187], v[220:223], v[64:67]
	s_barrier
	s_setprio 0
	s_add_i32 s0, s0, s41
	s_add_u32 s100, s36, 0x80
	s_addc_u32 s101, s37, 0
	s_mov_b32 m0, s0
	ds_read_b128 v[188:191], v158 offset:49152
	global_load_lds_dwordx4 v132, s[100:101]
	s_add_i32 m0, s0, 0x2000
	ds_read_b128 v[192:195], v158 offset:50176
	global_load_lds_dwordx4 v136, s[100:101]
	s_add_u32 s36, s36, 0x100080
	s_addc_u32 s37, s37, 0
	s_add_i32 s0, s1, s41
	s_mov_b32 m0, s0
	ds_read_b128 v[196:199], v158 offset:51200
	global_load_lds_dwordx4 v132, s[36:37]
	s_add_i32 m0, s0, 0x2000
	ds_read_b128 v[200:203], v158 offset:52224
	global_load_lds_dwordx4 v136, s[36:37]
	s_add_u32 s100, s38, 0xfff00080
	s_addc_u32 s101, s39, -1
	s_mov_b32 m0, s46
	ds_read_b128 v[208:211], v158 offset:53248
	global_load_lds_dwordx4 v130, s[100:101]
	s_mov_b32 m0, s47
	ds_read_b128 v[212:215], v158 offset:54272
	global_load_lds_dwordx4 v134, s[100:101]
	ds_read_b128 v[216:219], v158 offset:55296
	ds_read_b128 v[220:223], v158 offset:56320
	s_waitcnt vmcnt(8)
	s_waitcnt lgkmcnt(0)
	s_setprio 3
	s_barrier
	v_mfma_f32_16x16x32_bf16 v[60:63], v[148:151], v[188:191], v[60:63]
	v_mfma_f32_16x16x32_bf16 v[56:59], v[164:167], v[188:191], v[56:59]
	v_mfma_f32_16x16x32_bf16 v[44:47], v[148:151], v[196:199], v[44:47]
	v_mfma_f32_16x16x32_bf16 v[40:43], v[164:167], v[196:199], v[40:43]
	v_mfma_f32_16x16x32_bf16 v[28:31], v[148:151], v[208:211], v[28:31]
	v_mfma_f32_16x16x32_bf16 v[24:27], v[164:167], v[208:211], v[24:27]
	v_mfma_f32_16x16x32_bf16 v[12:15], v[148:151], v[216:219], v[12:15]
	v_mfma_f32_16x16x32_bf16 v[8:11], v[164:167], v[216:219], v[8:11]
	v_mfma_f32_16x16x32_bf16 v[60:63], v[160:163], v[192:195], v[60:63]
	v_mfma_f32_16x16x32_bf16 v[56:59], v[168:171], v[192:195], v[56:59]
	v_mfma_f32_16x16x32_bf16 v[44:47], v[160:163], v[200:203], v[44:47]
	v_mfma_f32_16x16x32_bf16 v[40:43], v[168:171], v[200:203], v[40:43]
	v_mfma_f32_16x16x32_bf16 v[28:31], v[160:163], v[212:215], v[28:31]
	v_mfma_f32_16x16x32_bf16 v[24:27], v[168:171], v[212:215], v[24:27]
	v_mfma_f32_16x16x32_bf16 v[12:15], v[160:163], v[220:223], v[12:15]
	v_mfma_f32_16x16x32_bf16 v[8:11], v[168:171], v[220:223], v[8:11]
	s_setprio 0
	s_setprio 3
	v_mfma_f32_16x16x32_bf16 v[52:55], v[172:175], v[188:191], v[52:55]
	v_mfma_f32_16x16x32_bf16 v[48:51], v[180:183], v[188:191], v[48:51]
	v_mfma_f32_16x16x32_bf16 v[36:39], v[172:175], v[196:199], v[36:39]
	v_mfma_f32_16x16x32_bf16 v[32:35], v[180:183], v[196:199], v[32:35]
	v_mfma_f32_16x16x32_bf16 v[20:23], v[172:175], v[208:211], v[20:23]
	v_mfma_f32_16x16x32_bf16 v[16:19], v[180:183], v[208:211], v[16:19]
	v_mfma_f32_16x16x32_bf16 v[4:7], v[172:175], v[216:219], v[4:7]
	v_mfma_f32_16x16x32_bf16 v[0:3], v[180:183], v[216:219], v[0:3]
	v_mfma_f32_16x16x32_bf16 v[52:55], v[176:179], v[192:195], v[52:55]
	v_mfma_f32_16x16x32_bf16 v[48:51], v[184:187], v[192:195], v[48:51]
	v_mfma_f32_16x16x32_bf16 v[36:39], v[176:179], v[200:203], v[36:39]
	v_mfma_f32_16x16x32_bf16 v[32:35], v[184:187], v[200:203], v[32:35]
	v_mfma_f32_16x16x32_bf16 v[20:23], v[176:179], v[212:215], v[20:23]
	v_mfma_f32_16x16x32_bf16 v[16:19], v[184:187], v[212:215], v[16:19]
	v_mfma_f32_16x16x32_bf16 v[4:7], v[176:179], v[220:223], v[4:7]
	v_mfma_f32_16x16x32_bf16 v[0:3], v[184:187], v[220:223], v[0:3]
	s_barrier
	s_setprio 0
	s_add_u32 s34, s34, 0x100
	s_addc_u32 s35, s35, 0
	s_add_i32 s60, s60, 2
	s_add_u32 s58, s58, 0x100
	s_addc_u32 s59, s59, 0
	s_cmp_gt_u32 s60, 61
	s_cbranch_scc0 .LBB0_134
	s_and_b64 vcc, exec, s[10:11]
	s_cbranch_vccz .LBB0_137
	s_barrier

	.amdhsa_kernel _Z8mega_fwd4Args
		.amdhsa_group_segment_fixed_size 0
		.amdhsa_private_segment_fixed_size 0
		.amdhsa_kernarg_size 464
		.amdhsa_user_sgpr_count 2
		.amdhsa_user_sgpr_dispatch_ptr 0
		.amdhsa_user_sgpr_queue_ptr 0
		.amdhsa_user_sgpr_kernarg_segment_ptr 1
		.amdhsa_user_sgpr_dispatch_id 0
		.amdhsa_user_sgpr_kernarg_preload_length 0
		.amdhsa_user_sgpr_kernarg_preload_offset 0
		.amdhsa_user_sgpr_private_segment_size 0
		.amdhsa_uses_dynamic_stack 0
		.amdhsa_enable_private_segment 0
		.amdhsa_system_sgpr_workgroup_id_x 1
		.amdhsa_system_sgpr_workgroup_id_y 0
		.amdhsa_system_sgpr_workgroup_id_z 0
		.amdhsa_system_sgpr_workgroup_info 0
		.amdhsa_system_vgpr_workitem_id 0
		.amdhsa_next_free_vgpr 256
		.amdhsa_next_free_sgpr 102
		.amdhsa_accum_offset 256
		.amdhsa_reserve_vcc 1
		.amdhsa_float_round_mode_32 0
		.amdhsa_float_round_mode_16_64 0
		.amdhsa_float_denorm_mode_32 3
		.amdhsa_float_denorm_mode_16_64 3
		.amdhsa_dx10_clamp 1
		.amdhsa_ieee_mode 1
		.amdhsa_fp16_overflow 0
		.amdhsa_tg_split 0
		.amdhsa_exception_fp_ieee_invalid_op 0
		.amdhsa_exception_fp_denorm_src 0
		.amdhsa_exception_fp_ieee_div_zero 0
		.amdhsa_exception_fp_ieee_overflow 0
		.amdhsa_exception_fp_ieee_underflow 0
		.amdhsa_exception_fp_ieee_inexact 0
		.amdhsa_exception_int_div_zero 0
	.end_amdhsa_kernel

.Lfunc_end0:
	.size	_Z8mega_fwd4Args, .Lfunc_end0-_Z8mega_fwd4Args
	.set _Z8mega_fwd4Args.num_vgpr, 256
	.set _Z8mega_fwd4Args.num_agpr, 0
	.set _Z8mega_fwd4Args.numbered_sgpr, 102
	.set _Z8mega_fwd4Args.num_named_barrier, 0
	.set _Z8mega_fwd4Args.private_seg_size, 0
	.set _Z8mega_fwd4Args.uses_vcc, 1
	.set _Z8mega_fwd4Args.uses_flat_scratch, 0
	.set _Z8mega_fwd4Args.has_dyn_sized_stack, 0
	.set _Z8mega_fwd4Args.has_recursion, 0
	.set _Z8mega_fwd4Args.has_indirect_call, 0

amdhsa.kernels:
  - .agpr_count:     0
    .args:
      - .offset:         0
        .size:           208
        .value_kind:     by_value
      - .offset:         208
        .size:           4
        .value_kind:     hidden_block_count_x
      - .offset:         212
        .size:           4
        .value_kind:     hidden_block_count_y
      - .offset:         216
        .size:           4
        .value_kind:     hidden_block_count_z
      - .offset:         220
        .size:           2
        .value_kind:     hidden_group_size_x
      - .offset:         222
        .size:           2
        .value_kind:     hidden_group_size_y
      - .offset:         224
        .size:           2
        .value_kind:     hidden_group_size_z
      - .offset:         226
        .size:           2
        .value_kind:     hidden_remainder_x
      - .offset:         228
        .size:           2
        .value_kind:     hidden_remainder_y
      - .offset:         230
        .size:           2
        .value_kind:     hidden_remainder_z
      - .offset:         248
        .size:           8
        .value_kind:     hidden_global_offset_x
      - .offset:         256
        .size:           8
        .value_kind:     hidden_global_offset_y
      - .offset:         264
        .size:           8
        .value_kind:     hidden_global_offset_z
      - .offset:         272
        .size:           2
        .value_kind:     hidden_grid_dims
      - .offset:         328
        .size:           4
        .value_kind:     hidden_dynamic_lds_size
    .group_segment_fixed_size: 0
    .kernarg_segment_align: 8
    .kernarg_segment_size: 464
    .language:       OpenCL C
    .language_version:
      - 2
      - 0
    .max_flat_workgroup_size: 512
    .name:           _Z8mega_fwd4Args
    .private_segment_fixed_size: 0
    .sgpr_count:     108
    .sgpr_spill_count: 15
    .symbol:         _Z8mega_fwd4Args.kd
    .uniform_work_group_size: 1
    .uses_dynamic_stack: false
    .vgpr_count:     256
    .vgpr_spill_count: 0
    .wavefront_size: 64
